# stack: v066 plus QKV SGPR-base DMA, tile-first LDS reads hoisted above tile decode, FFN-in 4-barrier per-half loop
# speedup vs baseline: 1.0002x; 1.0002x over previous
.LBB0_1564:
	s_ashr_i32 s9, s8, 31
	s_lshl_b64 s[10:11], s[8:9], 20
	v_readlane_b32 s12, v253, 25
	v_readlane_b32 s13, v253, 26
	s_add_u32 s10, s12, s10
	s_addc_u32 s11, s13, s11
	s_and_b64 s[12:13], s[34:35], exec
	s_cselect_b32 s9, s11, s19
	s_cselect_b32 s15, s10, s18
	s_ashr_i32 s7, s6, 31
	s_lshl_b64 s[12:13], s[6:7], 20
	s_add_u32 s12, s37, s12
	s_addc_u32 s13, s38, s13
	s_and_b64 s[22:23], s[34:35], exec
	s_cselect_b32 s7, s13, s21
	s_cselect_b32 s50, s12, s20
	s_add_u32 s18, s18, 0x80080
	s_addc_u32 s19, s19, 0
	s_add_u32 s51, s20, 0x100
	s_addc_u32 s52, s21, 0
	s_mov_b32 s53, -2
	s_add_u32 s20, s18, 0xfff80080
	s_addc_u32 s21, s19, -1
	s_add_i32 s54, 0, 0x10000
	s_cmp_eq_u32 s53, 28
	s_cselect_b32 s23, s9, s21
	s_cselect_b32 s22, s15, s20
	s_cselect_b32 s21, s7, s52
	s_cselect_b32 s20, s50, s51
	s_add_i32 s56, 0, 0x14000
	v_lshl_add_u64 v[158:159], s[18:19], 0, v[154:155]
	s_add_i32 m0, s17, 0xc000
	global_load_lds_dwordx4 v[158:159], off
	v_lshl_add_u64 v[158:159], s[18:19], 0, v[156:157]
	s_add_i32 m0, s17, 0xe000
	s_nop 0
	global_load_lds_dwordx4 v[158:159], off
	s_waitcnt vmcnt(8)
	s_waitcnt lgkmcnt(0)
	s_setprio 1
	s_and_b64 vcc, exec, s[4:5]
	s_cbranch_vccz .Lpk4_0
	s_barrier
